# combine and convfix stores write-through; leader write-back skipped after those phases too
# baseline (speedup 1.0000x reference)
.LBB0_71:
	s_or_b64 exec, exec, s[12:13]
	v_ashrrev_i32_e32 v5, 31, v4
	v_lshlrev_b64 v[8:9], 2, v[4:5]
	v_lshl_add_u64 v[12:13], s[6:7], 0, v[8:9]
	v_add_co_u32_e32 v22, vcc, 0x5000, v12
	global_load_dword v14, v[12:13], off
	s_nop 0
	v_addc_co_u32_e32 v23, vcc, 0, v13, vcc
	global_load_dword v21, v[22:23], off offset:2048
	v_add_co_u32_e32 v22, vcc, 0xb000, v12
	v_add_u32_e32 v2, 0xb00, v4
	s_nop 0
	v_addc_co_u32_e32 v23, vcc, 0, v13, vcc
	global_load_dword v15, v[22:23], off
	v_lshl_add_u64 v[24:25], s[8:9], 0, v[8:9]
	global_load_dword v30, v[24:25], off
	v_lshlrev_b64 v[24:25], 2, v[2:3]
	v_lshl_add_u64 v[26:27], s[6:7], 0, v[24:25]
	global_load_dword v31, v[26:27], off
	s_mov_b32 s2, 0x8000
	s_nop 0
	v_add_co_u32_e32 v26, vcc, s2, v12
	s_mov_b32 s2, 0xd000
	s_nop 0
	v_addc_co_u32_e32 v27, vcc, 0, v13, vcc
	v_add_co_u32_e32 v28, vcc, s2, v12
	global_load_dword v32, v[26:27], off offset:1024
	s_nop 0
	v_addc_co_u32_e32 v29, vcc, 0, v13, vcc
	global_load_dword v33, v[28:29], off offset:3072
	v_lshl_add_u64 v[24:25], s[8:9], 0, v[24:25]
	global_load_dword v34, v[24:25], off
	v_add_u32_e32 v16, s0, v16
	v_add_u32_e32 v17, s16, v17
	s_waitcnt vmcnt(0)
	v_pk_mul_f32 v[6:7], v[6:7], v[14:15]
	s_nop 0
	v_fma_f32 v6, v20, v21, v6
	v_add_f32_e32 v14, v6, v7
	v_add_f32_e32 v14, v30, v14
	v_pk_mul_f32 v[8:9], v[10:11], v[32:33]
	s_nop 0
	v_fma_f32 v2, v19, v31, v8
	v_add_f32_e32 v2, v2, v9
	v_add_f32_e32 v2, v34, v2
	v_mul_f32_e32 v6, 0xbfb8aa3b, v14
	v_exp_f32_e32 v6, v6
	s_nop 0
	v_add_f32_e32 v6, 1.0, v6
	v_div_scale_f32 v7, s[2:3], v6, v6, v14
	v_rcp_f32_e32 v8, v7
	v_readlane_b32 s2, v251, 12
	v_readlane_b32 s3, v251, 13
	v_fma_f32 v9, -v7, v8, 1.0
	v_fmac_f32_e32 v8, v9, v8
	v_div_scale_f32 v9, vcc, v14, v6, v14
	v_mul_f32_e32 v10, v9, v8
	v_fma_f32 v11, -v7, v10, v9
	v_fmac_f32_e32 v10, v11, v8
	v_fma_f32 v7, -v7, v10, v9
	v_div_fmas_f32 v7, v7, v8, v10
	v_div_fixup_f32 v6, v7, v6, v14
	v_mul_f32_e32 v2, v6, v2
	v_mov_b64_e32 v[6:7], s[2:3]
	s_movk_i32 s2, 0x1600
	v_mad_i64_i32 v[6:7], s[2:3], v18, s2, v[6:7]
	s_mov_b32 s2, 0x57fff
	s_nop 0
	v_cmp_lt_i32_e32 vcc, s2, v16
	v_cvt_pk_bf16_f32 v2, v2, s0
	v_lshl_add_u64 v[4:5], v[4:5], 1, v[6:7]
	s_or_b64 s[10:11], vcc, s[10:11]
	global_store_short v[4:5], v2, off sc1
	s_andn2_b64 exec, exec, s[10:11]
	s_cbranch_execz .LBB0_85

.LBB0_304:
	v_ashrrev_i32_e32 v6, 12, v4
	v_add_u32_e32 v7, 0x80, v6
	v_mul_hi_i32 v8, v7, s16
	v_lshrrev_b32_e32 v9, 31, v8
	v_ashrrev_i32_e32 v8, 4, v8
	v_add_u32_e32 v8, v8, v9
	v_mul_lo_u32 v9, v8, s17
	v_sub_u32_e32 v19, v7, v9
	v_ashrrev_i32_e32 v9, 31, v8
	v_lshlrev_b32_e32 v7, 8, v19
	v_bfe_u32 v2, v4, 4, 8
	v_lshlrev_b64 v[8:9], 12, v[8:9]
	v_and_b32_e32 v7, 0xf00, v7
	v_or3_b32 v8, v8, v7, v2
	v_ashrrev_i32_e32 v7, 31, v6
	v_lshlrev_b64 v[6:7], 8, v[6:7]
	v_or_b32_e32 v6, v6, v2
	v_lshl_add_u64 v[10:11], v[6:7], 0, s[10:11]
	v_lshlrev_b64 v[14:15], 11, v[8:9]
	v_lshl_add_u64 v[8:9], v[6:7], 3, s[14:15]
	v_lshl_add_u64 v[12:13], v[10:11], 3, s[14:15]
	global_load_dwordx2 v[8:9], v[8:9], off
	v_and_b32_e32 v18, 60, v5
	global_load_dwordx2 v[12:13], v[12:13], off
	v_lshlrev_b64 v[6:7], 8, v[6:7]
	v_lshlrev_b64 v[10:11], 8, v[10:11]
	v_lshl_add_u64 v[6:7], s[12:13], 0, v[6:7]
	v_lshl_add_u64 v[10:11], s[12:13], 0, v[10:11]
	v_add_u32_e32 v4, s0, v4
	s_mov_b32 s7, 0x3ffff
	v_add_u32_e32 v5, s6, v5
	v_lshlrev_b32_e32 v20, 2, v18
	v_mov_b32_e32 v21, 0
	v_lshl_add_u64 v[6:7], v[6:7], 0, v[20:21]
	v_lshl_add_u64 v[10:11], v[10:11], 0, v[20:21]
	global_load_dwordx4 v[22:25], v[6:7], off
	global_load_dwordx4 v[26:29], v[10:11], off
	s_waitcnt vmcnt(3)
	v_max_f32_e32 v2, v8, v8
	s_waitcnt vmcnt(2)
	v_max_f32_e32 v16, v12, v12
	v_max_f32_e32 v2, v2, v16
	v_sub_f32_e32 v8, v8, v2
	v_sub_f32_e32 v2, v12, v2
	v_exp_f32_e32 v16, v8
	v_exp_f32_e32 v17, v2
	v_mov_b32_e32 v12, v9
	v_pk_mul_f32 v[8:9], v[12:13], v[16:17]
	s_nop 0
	v_add_f32_e32 v2, v8, v9
	v_div_scale_f32 v12, s[8:9], v2, v2, 1.0
	v_rcp_f32_e32 v13, v12
	s_nop 0
	v_fma_f32 v16, -v12, v13, 1.0
	v_fmac_f32_e32 v13, v16, v13
	v_div_scale_f32 v16, vcc, 1.0, v2, 1.0
	v_mul_f32_e32 v17, v16, v13
	v_fma_f32 v20, -v12, v17, v16
	v_fmac_f32_e32 v17, v20, v13
	v_fma_f32 v12, -v12, v17, v16
	v_div_fmas_f32 v12, v12, v13, v17
	v_div_fixup_f32 v12, v12, v2, 1.0
	v_mul_f32_e32 v2, v8, v12
	v_mul_f32_e32 v16, v9, v12
	s_waitcnt vmcnt(0)
	v_pk_mul_f32 v[10:11], v[26:27], v[16:17] op_sel_hi:[1,0]
	s_nop 0
	v_pk_fma_f32 v[6:7], v[22:23], v[2:3], v[10:11] op_sel_hi:[1,0,1]
	v_pk_mul_f32 v[10:11], v[16:17], v[28:29] op_sel_hi:[0,1]
	v_pk_fma_f32 v[8:9], v[24:25], v[2:3], v[10:11] op_sel_hi:[1,0,1]
	v_lshlrev_b32_e32 v2, 2, v19
	v_and_b32_e32 v10, 0xffffffc0, v2
	v_cvt_pk_bf16_f32 v6, v6, v7
	v_cvt_pk_bf16_f32 v7, v8, v9
	v_lshl_add_u64 v[8:9], s[88:89], 0, v[14:15]
	v_ashrrev_i32_e32 v11, 31, v10
	v_lshl_add_u64 v[8:9], v[10:11], 1, v[8:9]
	v_lshlrev_b32_e32 v2, 1, v18
	v_lshl_add_u64 v[8:9], v[8:9], 0, v[2:3]
	v_add_co_u32_e32 v8, vcc, 0x11340000, v8
	s_nop 1
	v_addc_co_u32_e32 v9, vcc, 0, v9, vcc
	v_cmp_lt_i32_e32 vcc, s7, v4
	s_or_b64 s[4:5], vcc, s[4:5]
	global_store_dwordx2 v[8:9], v[6:7], off offset:1280 sc1
	s_andn2_b64 exec, exec, s[4:5]
	s_cbranch_execnz .LBB0_304

.Lxb_leader:
	v_readlane_b32 s98, v252, 2
	s_nop 0
	s_sub_i32 s98, s98, 4
	s_cmp_lt_i32 s98, 0
	s_cbranch_scc1 .Lxb_flush
	s_mul_i32 s99, s98, 0x1746
	s_lshr_b32 s99, s99, 16
	s_mul_i32 s99, s99, 11
	s_sub_i32 s98, s98, s99
	s_lshl_b32 s98, 1, s98
	s_and_b32 s98, s98, 0x7f0
	s_cmp_lg_u32 s98, 0
	s_cbranch_scc1 .Lxb_noflush
